# v58 + attention mid section: the two canonicalising v_max x,x,x after each row-max permlane swap dropped (5 sites); the mid section is on the step's critical path
# baseline (speedup 1.0000x reference)
.LBB0_1604:
	v_add_u32_e32 v0, s22, v244
	ds_read_b64_tr_b16 v[208:209], v0 offset:24576
	ds_read_b64_tr_b16 v[210:211], v0 offset:25088
	s_waitcnt lgkmcnt(9)
	v_mfma_f32_32x32x16_bf16 v[112:127], v[204:207], v[172:175], 0
	v_add_f32_e32 v2, v87, v88
	v_cvt_pk_bf16_f32 v156, v96, v97
	v_cvt_pk_bf16_f32 v157, v98, v99
	ds_read_b64_tr_b16 v[204:205], v0 offset:28672
	ds_read_b64_tr_b16 v[206:207], v0 offset:29184
	v_add_f32_e32 v2, v89, v2
	v_cvt_pk_bf16_f32 v158, v100, v101
	v_cvt_pk_bf16_f32 v159, v102, v103
	s_waitcnt lgkmcnt(10)
	v_mfma_f32_32x32x16_bf16 v[128:143], v[200:203], v[172:175], 0
	ds_read_b64_tr_b16 v[10:11], v0 offset:25600
	ds_read_b64_tr_b16 v[12:13], v0 offset:26112
	s_waitcnt lgkmcnt(11)
	v_mfma_f32_32x32x16_bf16 v[112:127], v[196:199], v[168:171], v[112:127]
	v_add_f32_e32 v2, v90, v2
	v_cvt_pk_bf16_f32 v152, v104, v105
	v_cvt_pk_bf16_f32 v153, v106, v107
	ds_read_b64_tr_b16 v[6:7], v0 offset:29696
	ds_read_b64_tr_b16 v[8:9], v0 offset:30208
	v_add_f32_e32 v14, v91, v2
	v_cvt_pk_bf16_f32 v154, v108, v109
	v_cvt_pk_bf16_f32 v155, v110, v111
	s_waitcnt lgkmcnt(12)
	v_mfma_f32_32x32x16_bf16 v[128:143], v[192:195], v[168:171], v[128:143]
	ds_read_b64_tr_b16 v[2:3], v0 offset:26624
	ds_read_b64_tr_b16 v[4:5], v0 offset:27136
	s_waitcnt lgkmcnt(13)
	v_mfma_f32_32x32x16_bf16 v[112:127], v[188:191], v[164:167], v[112:127]
	v_add_f32_e32 v14, v92, v14
	v_cvt_pk_bf16_f32 v148, v80, v81
	v_cvt_pk_bf16_f32 v149, v82, v83
	ds_read_b64_tr_b16 v[196:197], v0 offset:30720
	ds_read_b64_tr_b16 v[198:199], v0 offset:31232
	v_add_f32_e32 v14, v93, v14
	v_cvt_pk_bf16_f32 v150, v84, v85
	v_cvt_pk_bf16_f32 v151, v86, v87
	s_waitcnt lgkmcnt(14)
	v_mfma_f32_32x32x16_bf16 v[128:143], v[184:187], v[164:167], v[128:143]
	ds_read_b64_tr_b16 v[192:193], v0 offset:27648
	ds_read_b64_tr_b16 v[194:195], v0 offset:28160
	s_waitcnt lgkmcnt(14)
	v_mfma_f32_32x32x16_bf16 v[112:127], v[180:183], v[160:163], v[112:127]
	v_add_f32_e32 v14, v94, v14
	v_cvt_pk_bf16_f32 v144, v88, v89
	v_cvt_pk_bf16_f32 v145, v90, v91
	ds_read_b64_tr_b16 v[188:189], v0 offset:31744
	ds_read_b64_tr_b16 v[190:191], v0 offset:32256
	v_add_f32_e32 v96, v95, v14
	v_cvt_pk_bf16_f32 v146, v92, v93
	v_cvt_pk_bf16_f32 v147, v94, v95
	v_mfma_f32_32x32x16_bf16 v[128:143], v[176:179], v[160:163], v[128:143]
	s_nop 2
	v_add_f32_e64 v80, v112, -v228
	v_add_f32_e64 v81, v113, -v228
	s_nop 6
	v_pk_add_f32 v[14:15], v[128:129], v[228:229] op_sel_hi:[1,0] neg_lo:[0,1] neg_hi:[0,1]
	v_pk_add_f32 v[98:99], v[114:115], v[228:229] op_sel_hi:[1,0] neg_lo:[0,1] neg_hi:[0,1]
	v_pk_add_f32 v[82:83], v[130:131], v[228:229] op_sel_hi:[1,0] neg_lo:[0,1] neg_hi:[0,1]
	v_max_f32_e32 v97, v80, v81
	v_pk_add_f32 v[100:101], v[116:117], v[228:229] op_sel_hi:[1,0] neg_lo:[0,1] neg_hi:[0,1]
	v_pk_add_f32 v[102:103], v[118:119], v[228:229] op_sel_hi:[1,0] neg_lo:[0,1] neg_hi:[0,1]
	v_max3_f32 v112, v98, v99, v15
	v_max3_f32 v97, v97, v14, v82
	s_add_u32 s30, s16, s10
	v_pk_add_f32 v[84:85], v[132:133], v[228:229] op_sel_hi:[1,0] neg_lo:[0,1] neg_hi:[0,1]
	v_pk_add_f32 v[86:87], v[134:135], v[228:229] op_sel_hi:[1,0] neg_lo:[0,1] neg_hi:[0,1]
	v_max3_f32 v97, v97, v83, v100
	v_max3_f32 v112, v112, v102, v103
	s_addc_u32 s31, s17, s11
	v_pk_add_f32 v[104:105], v[120:121], v[228:229] op_sel_hi:[1,0] neg_lo:[0,1] neg_hi:[0,1]
	v_pk_add_f32 v[106:107], v[122:123], v[228:229] op_sel_hi:[1,0] neg_lo:[0,1] neg_hi:[0,1]
	v_max3_f32 v97, v97, v101, v84
	v_max3_f32 v112, v112, v86, v87
	s_add_u32 s22, s30, 0x80000
	v_pk_add_f32 v[88:89], v[136:137], v[228:229] op_sel_hi:[1,0] neg_lo:[0,1] neg_hi:[0,1]
	v_pk_add_f32 v[90:91], v[138:139], v[228:229] op_sel_hi:[1,0] neg_lo:[0,1] neg_hi:[0,1]
	v_max3_f32 v97, v97, v85, v104
	v_max3_f32 v112, v112, v106, v107
	s_addc_u32 s23, s31, 0
	s_add_i32 s24, s29, s57
	v_pk_add_f32 v[108:109], v[124:125], v[228:229] op_sel_hi:[1,0] neg_lo:[0,1] neg_hi:[0,1]
	v_pk_add_f32 v[110:111], v[126:127], v[228:229] op_sel_hi:[1,0] neg_lo:[0,1] neg_hi:[0,1]
	v_max3_f32 v97, v97, v105, v88
	v_max3_f32 v112, v112, v90, v91
	s_add_u32 s62, s18, s10
	v_pk_add_f32 v[92:93], v[140:141], v[228:229] op_sel_hi:[1,0] neg_lo:[0,1] neg_hi:[0,1]
	v_pk_add_f32 v[94:95], v[142:143], v[228:229] op_sel_hi:[1,0] neg_lo:[0,1] neg_hi:[0,1]
	v_max3_f32 v97, v97, v89, v108
	v_max3_f32 v112, v112, v110, v111
	s_addc_u32 s63, s19, s11
	v_max3_f32 v97, v97, v109, v92
	v_max3_f32 v112, v112, v94, v95
	s_mov_b32 s25, m0
	s_mov_b32 m0, s24
	s_nop 0
	global_load_lds_dwordx4 v241, s[22:23]
	s_mov_b32 m0, s25
	s_add_u32 s22, s62, 0x40000
	v_add_f32_e32 v116, v224, v96
	v_max3_f32 v96, v97, v93, v112
	s_addc_u32 s23, s63, 0
	s_add_i32 s24, s28, s58
	v_mov_b32_e32 v97, v96
	s_add_u32 s64, s20, s10
	s_nop 0
	v_permlane32_swap_b32_e32 v96, v97
	s_addc_u32 s65, s21, s11
	s_mov_b32 s25, m0
	s_mov_b32 m0, s24
	s_nop 0
	global_load_lds_dwordx4 v242, s[22:23]
	s_mov_b32 m0, s25
	s_add_u32 s22, s64, 0x40000
	v_max_f32_e32 v96, v96, v97
	s_addc_u32 s23, s65, 0
	s_add_i32 s24, s28, s59
	s_mov_b32 s25, m0
	s_mov_b32 m0, s24
	s_nop 0
	global_load_lds_dwordx4 v242, s[22:23]
	s_mov_b32 m0, s25
	v_cmp_lt_f32_e32 vcc, s35, v96
	s_cmp_lg_u64 vcc, 0
	s_cselect_b64 s[22:23], -1, 0
	s_cbranch_vccnz .LBB0_1612

.LBB0_1607:
	s_add_i32 s22, s28, 0x2000
	s_cmpk_lg_i32 s28, 0x4000
	s_cselect_b32 s61, s22, 0
	v_add_f32_e32 v15, v116, v14
	v_add_u32_e32 v14, s29, v244
	ds_read_b64_tr_b16 v[196:197], v14 offset:24576
	ds_read_b64_tr_b16 v[198:199], v14 offset:25088
	v_add_f32_e32 v132, v87, v88
	v_cvt_pk_bf16_f32 v156, v96, v97
	v_cvt_pk_bf16_f32 v157, v98, v99
	v_mfma_f32_32x32x16_bf16 v[112:127], v[112:115], v[172:175], 0
	ds_read_b64_tr_b16 v[192:193], v14 offset:28672
	ds_read_b64_tr_b16 v[194:195], v14 offset:29184
	v_add_f32_e32 v96, v89, v132
	v_cvt_pk_bf16_f32 v158, v100, v101
	v_cvt_pk_bf16_f32 v159, v102, v103
	v_mfma_f32_32x32x16_bf16 v[128:143], v[128:131], v[172:175], 0
	ds_read_b64_tr_b16 v[188:189], v14 offset:25600
	ds_read_b64_tr_b16 v[190:191], v14 offset:26112
	v_add_f32_e32 v96, v90, v96
	v_cvt_pk_bf16_f32 v152, v104, v105
	v_cvt_pk_bf16_f32 v153, v106, v107
	v_mfma_f32_32x32x16_bf16 v[112:127], v[184:187], v[168:171], v[112:127]
	ds_read_b64_tr_b16 v[184:185], v14 offset:29696
	ds_read_b64_tr_b16 v[186:187], v14 offset:30208
	v_add_f32_e32 v96, v91, v96
	v_cvt_pk_bf16_f32 v154, v108, v109
	v_cvt_pk_bf16_f32 v155, v110, v111
	v_mfma_f32_32x32x16_bf16 v[128:143], v[176:179], v[168:171], v[128:143]
	ds_read_b64_tr_b16 v[176:177], v14 offset:26624
	ds_read_b64_tr_b16 v[178:179], v14 offset:27136
	v_add_f32_e32 v96, v92, v96
	v_cvt_pk_bf16_f32 v148, v80, v81
	v_cvt_pk_bf16_f32 v149, v82, v83
	v_mfma_f32_32x32x16_bf16 v[112:127], v[180:183], v[164:167], v[112:127]
	ds_read_b64_tr_b16 v[212:213], v14 offset:30720
	ds_read_b64_tr_b16 v[214:215], v14 offset:31232
	v_add_f32_e32 v80, v93, v96
	v_cvt_pk_bf16_f32 v150, v84, v85
	v_cvt_pk_bf16_f32 v151, v86, v87
	v_mfma_f32_32x32x16_bf16 v[128:143], v[6:9], v[164:167], v[128:143]
	ds_read_b64_tr_b16 v[208:209], v14 offset:27648
	ds_read_b64_tr_b16 v[210:211], v14 offset:28160
	v_add_f32_e32 v80, v94, v80
	v_cvt_pk_bf16_f32 v144, v88, v89
	v_cvt_pk_bf16_f32 v145, v90, v91
	v_mfma_f32_32x32x16_bf16 v[112:127], v[10:13], v[160:163], v[112:127]
	ds_read_b64_tr_b16 v[6:7], v14 offset:31744
	ds_read_b64_tr_b16 v[8:9], v14 offset:32256
	v_add_f32_e32 v10, v95, v80
	v_cvt_pk_bf16_f32 v146, v92, v93
	v_cvt_pk_bf16_f32 v147, v94, v95
	v_mfma_f32_32x32x16_bf16 v[128:143], v[2:5], v[160:163], v[128:143]
	s_nop 5
	v_add_f32_e64 v4, v112, -v228
	v_add_f32_e64 v5, v113, -v228
	s_nop 3
	v_pk_add_f32 v[2:3], v[128:129], v[228:229] op_sel_hi:[1,0] neg_lo:[0,1] neg_hi:[0,1]
	v_pk_add_f32 v[98:99], v[114:115], v[228:229] op_sel_hi:[1,0] neg_lo:[0,1] neg_hi:[0,1]
	v_pk_add_f32 v[82:83], v[130:131], v[228:229] op_sel_hi:[1,0] neg_lo:[0,1] neg_hi:[0,1]
	v_max_f32_e32 v11, v4, v5
	v_pk_add_f32 v[100:101], v[116:117], v[228:229] op_sel_hi:[1,0] neg_lo:[0,1] neg_hi:[0,1]
	v_pk_add_f32 v[102:103], v[118:119], v[228:229] op_sel_hi:[1,0] neg_lo:[0,1] neg_hi:[0,1]
	v_max3_f32 v12, v98, v99, v3
	v_max3_f32 v11, v11, v2, v82
	v_pk_add_f32 v[84:85], v[132:133], v[228:229] op_sel_hi:[1,0] neg_lo:[0,1] neg_hi:[0,1]
	v_pk_add_f32 v[86:87], v[134:135], v[228:229] op_sel_hi:[1,0] neg_lo:[0,1] neg_hi:[0,1]
	v_max3_f32 v11, v11, v83, v100
	v_max3_f32 v12, v12, v102, v103
	v_pk_add_f32 v[104:105], v[120:121], v[228:229] op_sel_hi:[1,0] neg_lo:[0,1] neg_hi:[0,1]
	v_pk_add_f32 v[106:107], v[122:123], v[228:229] op_sel_hi:[1,0] neg_lo:[0,1] neg_hi:[0,1]
	v_max3_f32 v11, v11, v101, v84
	v_max3_f32 v12, v12, v86, v87
	v_pk_add_f32 v[88:89], v[136:137], v[228:229] op_sel_hi:[1,0] neg_lo:[0,1] neg_hi:[0,1]
	v_pk_add_f32 v[90:91], v[138:139], v[228:229] op_sel_hi:[1,0] neg_lo:[0,1] neg_hi:[0,1]
	v_max3_f32 v11, v11, v85, v104
	v_max3_f32 v12, v12, v106, v107
	v_pk_add_f32 v[108:109], v[124:125], v[228:229] op_sel_hi:[1,0] neg_lo:[0,1] neg_hi:[0,1]
	v_pk_add_f32 v[110:111], v[126:127], v[228:229] op_sel_hi:[1,0] neg_lo:[0,1] neg_hi:[0,1]
	v_max3_f32 v11, v11, v105, v88
	v_max3_f32 v12, v12, v90, v91
	v_pk_add_f32 v[92:93], v[140:141], v[228:229] op_sel_hi:[1,0] neg_lo:[0,1] neg_hi:[0,1]
	v_pk_add_f32 v[94:95], v[142:143], v[228:229] op_sel_hi:[1,0] neg_lo:[0,1] neg_hi:[0,1]
	v_max3_f32 v11, v11, v89, v108
	v_max3_f32 v12, v12, v110, v111
	v_max3_f32 v11, v11, v109, v92
	v_max3_f32 v12, v12, v94, v95
	s_add_u32 s22, s30, 0xa0000
	v_max3_f32 v11, v11, v93, v12
	s_addc_u32 s23, s31, 0
	s_add_i32 s24, s28, s57
	v_mov_b32_e32 v12, v11
	s_mov_b32 s25, m0
	s_mov_b32 m0, s24
	s_nop 0
	global_load_lds_dwordx4 v241, s[22:23]
	s_mov_b32 m0, s25
	s_add_u32 s22, s62, 0x60000
	s_nop 0
	v_permlane32_swap_b32_e32 v11, v12
	s_addc_u32 s23, s63, 0
	s_add_i32 s24, s61, s58
	s_mov_b32 s25, m0
	s_mov_b32 m0, s24
	s_nop 0
	global_load_lds_dwordx4 v242, s[22:23]
	s_mov_b32 m0, s25
	s_add_u32 s22, s64, 0x60000
	v_max_f32_e32 v11, v11, v12
	s_addc_u32 s23, s65, 0
	s_add_i32 s24, s61, s59
	s_mov_b32 s25, m0
	s_mov_b32 m0, s24
	s_nop 0
	global_load_lds_dwordx4 v242, s[22:23]
	s_mov_b32 m0, s25
	v_cmp_lt_f32_e32 vcc, s35, v11
	s_cmp_lg_u64 vcc, 0
	v_add_f32_e32 v10, v15, v10
	s_cselect_b64 s[22:23], -1, 0
	s_cbranch_vccnz .LBB0_1615

.LBB0_1620:
	v_add_u32_e32 v212, s62, v244
	ds_read_b64_tr_b16 v[208:209], v212 offset:24576
	ds_read_b64_tr_b16 v[210:211], v212 offset:25088
	v_add_f32_e32 v0, v87, v88
	v_cvt_pk_bf16_f32 v156, v96, v97
	v_cvt_pk_bf16_f32 v157, v98, v99
	s_waitcnt lgkmcnt(9)
	v_mfma_f32_32x32x16_bf16 v[112:127], v[204:207], v[172:175], 0
	ds_read_b64_tr_b16 v[204:205], v212 offset:28672
	ds_read_b64_tr_b16 v[206:207], v212 offset:29184
	v_add_f32_e32 v0, v89, v0
	v_cvt_pk_bf16_f32 v158, v100, v101
	v_cvt_pk_bf16_f32 v159, v102, v103
	s_waitcnt lgkmcnt(10)
	v_mfma_f32_32x32x16_bf16 v[128:143], v[200:203], v[172:175], 0
	ds_read_b64_tr_b16 v[200:201], v212 offset:25600
	ds_read_b64_tr_b16 v[202:203], v212 offset:26112
	v_add_f32_e32 v0, v90, v0
	v_cvt_pk_bf16_f32 v152, v104, v105
	v_cvt_pk_bf16_f32 v153, v106, v107
	s_waitcnt lgkmcnt(11)
	v_mfma_f32_32x32x16_bf16 v[112:127], v[196:199], v[168:171], v[112:127]
	ds_read_b64_tr_b16 v[172:173], v212 offset:29696
	ds_read_b64_tr_b16 v[174:175], v212 offset:30208
	v_add_f32_e32 v0, v91, v0
	v_cvt_pk_bf16_f32 v154, v108, v109
	v_cvt_pk_bf16_f32 v155, v110, v111
	s_waitcnt lgkmcnt(12)
	v_mfma_f32_32x32x16_bf16 v[128:143], v[192:195], v[168:171], v[128:143]
	ds_read_b64_tr_b16 v[168:169], v212 offset:26624
	ds_read_b64_tr_b16 v[170:171], v212 offset:27136
	v_add_f32_e32 v0, v92, v0
	v_cvt_pk_bf16_f32 v148, v80, v81
	v_cvt_pk_bf16_f32 v149, v82, v83
	s_waitcnt lgkmcnt(13)
	v_mfma_f32_32x32x16_bf16 v[112:127], v[188:191], v[164:167], v[112:127]
	ds_read_b64_tr_b16 v[10:11], v212 offset:30720
	ds_read_b64_tr_b16 v[12:13], v212 offset:31232
	v_add_f32_e32 v0, v93, v0
	v_cvt_pk_bf16_f32 v150, v84, v85
	v_cvt_pk_bf16_f32 v151, v86, v87
	s_waitcnt lgkmcnt(14)
	v_mfma_f32_32x32x16_bf16 v[128:143], v[184:187], v[164:167], v[128:143]
	ds_read_b64_tr_b16 v[6:7], v212 offset:27648
	ds_read_b64_tr_b16 v[8:9], v212 offset:28160
	v_add_f32_e32 v0, v94, v0
	v_cvt_pk_bf16_f32 v144, v88, v89
	v_cvt_pk_bf16_f32 v145, v90, v91
	s_waitcnt lgkmcnt(14)
	v_mfma_f32_32x32x16_bf16 v[112:127], v[180:183], v[160:163], v[112:127]
	ds_read_b64_tr_b16 v[2:3], v212 offset:31744
	ds_read_b64_tr_b16 v[4:5], v212 offset:32256
	v_add_f32_e32 v0, v95, v0
	v_cvt_pk_bf16_f32 v146, v92, v93
	v_cvt_pk_bf16_f32 v147, v94, v95
	v_mfma_f32_32x32x16_bf16 v[128:143], v[176:179], v[160:163], v[128:143]
	v_or_b32_e32 v14, 0xe0, v239
	v_or_b32_e32 v15, 0xc0, v239
	v_cmp_le_i32_e32 vcc, v14, v240
	v_or_b32_e32 v82, 0xc2, v239
	v_or_b32_e32 v83, 0xe2, v239
	s_nop 6
	v_cndmask_b32_e32 v14, v230, v128, vcc
	v_cmp_lt_i32_e32 vcc, v15, v240
	v_or_b32_e32 v85, 0xe3, v239
	v_or_b32_e32 v86, 0xc8, v239
	v_cndmask_b32_e32 v81, v230, v113, vcc
	v_cmp_le_i32_e32 vcc, v15, v240
	v_or_b32_e32 v15, 0xe1, v239
	v_or_b32_e32 v87, 0xe8, v239
	v_cndmask_b32_e32 v80, v230, v112, vcc
	v_cmp_le_i32_e32 vcc, v15, v240
	v_or_b32_e32 v89, 0xe9, v239
	v_or_b32_e32 v90, 0xca, v239
	v_cndmask_b32_e32 v15, v230, v129, vcc
	v_cmp_le_i32_e32 vcc, v82, v240
	v_or_b32_e32 v91, 0xea, v239
	v_or_b32_e32 v93, 0xeb, v239
	v_cndmask_b32_e32 v82, v230, v114, vcc
	v_cmp_le_i32_e32 vcc, v83, v240
	v_or_b32_e32 v83, 0xc3, v239
	v_or_b32_e32 v94, 0xd0, v239
	v_cndmask_b32_e32 v84, v230, v130, vcc
	v_cmp_le_i32_e32 vcc, v83, v240
	v_or_b32_e32 v95, 0xf0, v239
	v_or_b32_e32 v97, 0xf1, v239
	v_cndmask_b32_e32 v83, v230, v115, vcc
	v_cmp_le_i32_e32 vcc, v85, v240
	v_or_b32_e32 v98, 0xd2, v239
	v_pk_add_f32 v[80:81], v[80:81], v[228:229] op_sel_hi:[1,0] neg_lo:[0,1] neg_hi:[0,1]
	v_cndmask_b32_e32 v85, v230, v131, vcc
	v_cmp_le_i32_e32 vcc, v86, v240
	v_pk_add_f32 v[14:15], v[14:15], v[228:229] op_sel_hi:[1,0] neg_lo:[0,1] neg_hi:[0,1]
	v_add_f32_e32 v0, v224, v0
	v_cndmask_b32_e32 v86, v230, v116, vcc
	v_cmp_le_i32_e32 vcc, v87, v240
	v_or_b32_e32 v87, 0xc9, v239
	s_nop 0
	v_cndmask_b32_e32 v88, v230, v132, vcc
	v_cmp_le_i32_e32 vcc, v87, v240
	s_nop 1
	v_cndmask_b32_e32 v87, v230, v117, vcc
	v_cmp_le_i32_e32 vcc, v89, v240
	v_pk_add_f32 v[100:101], v[86:87], v[228:229] op_sel_hi:[1,0] neg_lo:[0,1] neg_hi:[0,1]
	s_nop 0
	v_cndmask_b32_e32 v89, v230, v133, vcc
	v_cmp_le_i32_e32 vcc, v90, v240
	s_nop 1
	v_cndmask_b32_e32 v90, v230, v118, vcc
	v_cmp_le_i32_e32 vcc, v91, v240
	v_or_b32_e32 v91, 0xcb, v239
	s_nop 0
	v_cndmask_b32_e32 v92, v230, v134, vcc
	v_cmp_le_i32_e32 vcc, v91, v240
	s_nop 1
	v_cndmask_b32_e32 v91, v230, v119, vcc
	v_cmp_le_i32_e32 vcc, v93, v240
	v_pk_add_f32 v[102:103], v[90:91], v[228:229] op_sel_hi:[1,0] neg_lo:[0,1] neg_hi:[0,1]
	s_nop 0
	v_cndmask_b32_e32 v93, v230, v135, vcc
	v_cmp_le_i32_e32 vcc, v94, v240
	v_pk_add_f32 v[86:87], v[92:93], v[228:229] op_sel_hi:[1,0] neg_lo:[0,1] neg_hi:[0,1]
	s_nop 0
	v_cndmask_b32_e32 v94, v230, v120, vcc
	v_cmp_le_i32_e32 vcc, v95, v240
	v_or_b32_e32 v95, 0xd1, v239
	s_nop 0
	v_cndmask_b32_e32 v96, v230, v136, vcc
	v_cmp_le_i32_e32 vcc, v95, v240
	s_nop 1
	v_cndmask_b32_e32 v95, v230, v121, vcc
	v_cmp_le_i32_e32 vcc, v97, v240
	v_pk_add_f32 v[104:105], v[94:95], v[228:229] op_sel_hi:[1,0] neg_lo:[0,1] neg_hi:[0,1]
	s_nop 0
	v_cndmask_b32_e32 v97, v230, v137, vcc
	v_cmp_le_i32_e32 vcc, v98, v240
	v_or_b32_e32 v98, 0xf2, v239
	s_nop 0
	v_cndmask_b32_e32 v106, v230, v122, vcc
	v_cmp_le_i32_e32 vcc, v98, v240
	v_or_b32_e32 v98, 0xd3, v239
	s_nop 0
	v_cndmask_b32_e32 v108, v230, v138, vcc
	v_cmp_le_i32_e32 vcc, v98, v240
	v_or_b32_e32 v98, 0xf3, v239
	s_nop 0
	v_cndmask_b32_e32 v107, v230, v123, vcc
	v_cmp_le_i32_e32 vcc, v98, v240
	v_or_b32_e32 v98, 0xd8, v239
	v_pk_add_f32 v[106:107], v[106:107], v[228:229] op_sel_hi:[1,0] neg_lo:[0,1] neg_hi:[0,1]
	v_cndmask_b32_e32 v109, v230, v139, vcc
	v_cmp_le_i32_e32 vcc, v98, v240
	v_or_b32_e32 v98, 0xf8, v239
	v_pk_add_f32 v[90:91], v[108:109], v[228:229] op_sel_hi:[1,0] neg_lo:[0,1] neg_hi:[0,1]
	v_cndmask_b32_e32 v110, v230, v124, vcc
	v_cmp_le_i32_e32 vcc, v98, v240
	v_or_b32_e32 v98, 0xd9, v239
	s_nop 0
	v_cndmask_b32_e32 v112, v230, v140, vcc
	v_cmp_le_i32_e32 vcc, v98, v240
	v_or_b32_e32 v98, 0xf9, v239
	s_nop 0
	v_cndmask_b32_e32 v111, v230, v125, vcc
	v_cmp_le_i32_e32 vcc, v98, v240
	v_or_b32_e32 v98, 0xda, v239
	v_pk_add_f32 v[108:109], v[110:111], v[228:229] op_sel_hi:[1,0] neg_lo:[0,1] neg_hi:[0,1]
	v_cndmask_b32_e32 v113, v230, v141, vcc
	v_cmp_le_i32_e32 vcc, v98, v240
	v_or_b32_e32 v98, 0xfa, v239
	v_pk_add_f32 v[92:93], v[112:113], v[228:229] op_sel_hi:[1,0] neg_lo:[0,1] neg_hi:[0,1]
	v_cndmask_b32_e32 v114, v230, v126, vcc
	v_cmp_le_i32_e32 vcc, v98, v240
	v_or_b32_e32 v98, 0xdb, v239
	s_nop 0
	v_cndmask_b32_e32 v116, v230, v142, vcc
	v_cmp_le_i32_e32 vcc, v98, v240
	v_or_b32_e32 v98, 0xfb, v239
	s_nop 0
	v_cndmask_b32_e32 v115, v230, v127, vcc
	v_cmp_le_i32_e32 vcc, v98, v240
	v_pk_add_f32 v[98:99], v[82:83], v[228:229] op_sel_hi:[1,0] neg_lo:[0,1] neg_hi:[0,1]
	v_pk_add_f32 v[82:83], v[84:85], v[228:229] op_sel_hi:[1,0] neg_lo:[0,1] neg_hi:[0,1]
	v_pk_add_f32 v[84:85], v[88:89], v[228:229] op_sel_hi:[1,0] neg_lo:[0,1] neg_hi:[0,1]
	v_pk_add_f32 v[88:89], v[96:97], v[228:229] op_sel_hi:[1,0] neg_lo:[0,1] neg_hi:[0,1]
	v_max_f32_e32 v96, v80, v81
	v_max3_f32 v97, v98, v99, v15
	v_max3_f32 v96, v96, v14, v82
	v_max3_f32 v96, v96, v83, v100
	v_max3_f32 v97, v97, v102, v103
	v_max3_f32 v96, v96, v101, v84
	v_max3_f32 v97, v97, v86, v87
	v_max3_f32 v96, v96, v85, v104
	v_max3_f32 v97, v97, v106, v107
	v_cndmask_b32_e32 v117, v230, v143, vcc
	v_pk_add_f32 v[110:111], v[114:115], v[228:229] op_sel_hi:[1,0] neg_lo:[0,1] neg_hi:[0,1]
	v_max3_f32 v96, v96, v105, v88
	v_max3_f32 v97, v97, v90, v91
	v_pk_add_f32 v[94:95], v[116:117], v[228:229] op_sel_hi:[1,0] neg_lo:[0,1] neg_hi:[0,1]
	v_max3_f32 v96, v96, v89, v108
	v_max3_f32 v97, v97, v110, v111
	v_max3_f32 v96, v96, v109, v92
	v_max3_f32 v97, v97, v94, v95
	v_max3_f32 v96, v96, v93, v97
	v_mov_b32_e32 v97, v96
	s_nop 1
	v_permlane32_swap_b32_e32 v96, v97
	v_max_f32_e32 v96, v96, v97
	v_cmp_lt_f32_e32 vcc, s35, v96
	s_cmp_lg_u64 vcc, 0
	s_cselect_b64 s[8:9], -1, 0
	s_cbranch_vccnz .LBB0_1675

.LBB0_1631:
	v_pk_add_f32 v[80:81], v[112:113], v[228:229] op_sel_hi:[1,0] neg_lo:[0,1] neg_hi:[0,1]
	v_add_f32_e32 v247, v224, v14
	v_pk_add_f32 v[14:15], v[128:129], v[228:229] op_sel_hi:[1,0] neg_lo:[0,1] neg_hi:[0,1]
	v_pk_add_f32 v[98:99], v[114:115], v[228:229] op_sel_hi:[1,0] neg_lo:[0,1] neg_hi:[0,1]
	v_pk_add_f32 v[82:83], v[130:131], v[228:229] op_sel_hi:[1,0] neg_lo:[0,1] neg_hi:[0,1]
	v_max_f32_e32 v96, v80, v81
	v_pk_add_f32 v[100:101], v[116:117], v[228:229] op_sel_hi:[1,0] neg_lo:[0,1] neg_hi:[0,1]
	v_pk_add_f32 v[102:103], v[118:119], v[228:229] op_sel_hi:[1,0] neg_lo:[0,1] neg_hi:[0,1]
	v_max3_f32 v97, v98, v99, v15
	v_max3_f32 v96, v96, v14, v82
	v_pk_add_f32 v[84:85], v[132:133], v[228:229] op_sel_hi:[1,0] neg_lo:[0,1] neg_hi:[0,1]
	v_pk_add_f32 v[86:87], v[134:135], v[228:229] op_sel_hi:[1,0] neg_lo:[0,1] neg_hi:[0,1]
	v_max3_f32 v96, v96, v83, v100
	v_max3_f32 v97, v97, v102, v103
	v_pk_add_f32 v[104:105], v[120:121], v[228:229] op_sel_hi:[1,0] neg_lo:[0,1] neg_hi:[0,1]
	v_pk_add_f32 v[106:107], v[122:123], v[228:229] op_sel_hi:[1,0] neg_lo:[0,1] neg_hi:[0,1]
	v_max3_f32 v96, v96, v101, v84
	v_max3_f32 v97, v97, v86, v87
	v_pk_add_f32 v[88:89], v[136:137], v[228:229] op_sel_hi:[1,0] neg_lo:[0,1] neg_hi:[0,1]
	v_pk_add_f32 v[90:91], v[138:139], v[228:229] op_sel_hi:[1,0] neg_lo:[0,1] neg_hi:[0,1]
	v_max3_f32 v96, v96, v85, v104
	v_max3_f32 v97, v97, v106, v107
	v_pk_add_f32 v[108:109], v[124:125], v[228:229] op_sel_hi:[1,0] neg_lo:[0,1] neg_hi:[0,1]
	v_pk_add_f32 v[110:111], v[126:127], v[228:229] op_sel_hi:[1,0] neg_lo:[0,1] neg_hi:[0,1]
	v_max3_f32 v96, v96, v105, v88
	v_max3_f32 v97, v97, v90, v91
	v_pk_add_f32 v[92:93], v[140:141], v[228:229] op_sel_hi:[1,0] neg_lo:[0,1] neg_hi:[0,1]
	v_pk_add_f32 v[94:95], v[142:143], v[228:229] op_sel_hi:[1,0] neg_lo:[0,1] neg_hi:[0,1]
	v_max3_f32 v96, v96, v89, v108
	v_max3_f32 v97, v97, v110, v111
	v_max3_f32 v96, v96, v109, v92
	v_max3_f32 v97, v97, v94, v95
	v_max3_f32 v96, v96, v93, v97
	v_mov_b32_e32 v97, v96
	s_nop 1
	v_permlane32_swap_b32_e32 v96, v97
	v_max_f32_e32 v96, v96, v97
	v_cmp_lt_f32_e32 vcc, s35, v96
	s_cmp_lg_u64 vcc, 0
	s_cselect_b64 s[10:11], -1, 0
	s_cbranch_vccnz .LBB0_1669

.LBB0_1642:
	v_add_f32_e32 v14, v247, v14
	v_pk_add_f32 v[80:81], v[112:113], v[228:229] op_sel_hi:[1,0] neg_lo:[0,1] neg_hi:[0,1]
	v_add_f32_e32 v247, v14, v15
	v_pk_add_f32 v[14:15], v[128:129], v[228:229] op_sel_hi:[1,0] neg_lo:[0,1] neg_hi:[0,1]
	v_pk_add_f32 v[98:99], v[114:115], v[228:229] op_sel_hi:[1,0] neg_lo:[0,1] neg_hi:[0,1]
	v_pk_add_f32 v[82:83], v[130:131], v[228:229] op_sel_hi:[1,0] neg_lo:[0,1] neg_hi:[0,1]
	v_max_f32_e32 v96, v80, v81
	v_pk_add_f32 v[100:101], v[116:117], v[228:229] op_sel_hi:[1,0] neg_lo:[0,1] neg_hi:[0,1]
	v_pk_add_f32 v[102:103], v[118:119], v[228:229] op_sel_hi:[1,0] neg_lo:[0,1] neg_hi:[0,1]
	v_max3_f32 v97, v98, v99, v15
	v_max3_f32 v96, v96, v14, v82
	v_pk_add_f32 v[84:85], v[132:133], v[228:229] op_sel_hi:[1,0] neg_lo:[0,1] neg_hi:[0,1]
	v_pk_add_f32 v[86:87], v[134:135], v[228:229] op_sel_hi:[1,0] neg_lo:[0,1] neg_hi:[0,1]
	v_max3_f32 v96, v96, v83, v100
	v_max3_f32 v97, v97, v102, v103
	v_pk_add_f32 v[104:105], v[120:121], v[228:229] op_sel_hi:[1,0] neg_lo:[0,1] neg_hi:[0,1]
	v_pk_add_f32 v[106:107], v[122:123], v[228:229] op_sel_hi:[1,0] neg_lo:[0,1] neg_hi:[0,1]
	v_max3_f32 v96, v96, v101, v84
	v_max3_f32 v97, v97, v86, v87
	v_pk_add_f32 v[88:89], v[136:137], v[228:229] op_sel_hi:[1,0] neg_lo:[0,1] neg_hi:[0,1]
	v_pk_add_f32 v[90:91], v[138:139], v[228:229] op_sel_hi:[1,0] neg_lo:[0,1] neg_hi:[0,1]
	v_max3_f32 v96, v96, v85, v104
	v_max3_f32 v97, v97, v106, v107
	v_pk_add_f32 v[108:109], v[124:125], v[228:229] op_sel_hi:[1,0] neg_lo:[0,1] neg_hi:[0,1]
	v_pk_add_f32 v[110:111], v[126:127], v[228:229] op_sel_hi:[1,0] neg_lo:[0,1] neg_hi:[0,1]
	v_max3_f32 v96, v96, v105, v88
	v_max3_f32 v97, v97, v90, v91
	v_pk_add_f32 v[92:93], v[140:141], v[228:229] op_sel_hi:[1,0] neg_lo:[0,1] neg_hi:[0,1]
	v_pk_add_f32 v[94:95], v[142:143], v[228:229] op_sel_hi:[1,0] neg_lo:[0,1] neg_hi:[0,1]
	v_max3_f32 v96, v96, v89, v108
	v_max3_f32 v97, v97, v110, v111
	v_max3_f32 v96, v96, v109, v92
	v_max3_f32 v97, v97, v94, v95
	v_max3_f32 v96, v96, v93, v97
	v_mov_b32_e32 v97, v96
	s_nop 1
	v_permlane32_swap_b32_e32 v96, v97
	v_max_f32_e32 v96, v96, v97
	v_cmp_lt_f32_e32 vcc, s35, v96
	s_cmp_lg_u64 vcc, 0
	s_cselect_b64 s[28:29], -1, 0
	s_cbranch_vccnz .LBB0_1672
